# QKV epilogue: row sum-of-squares all-reduce via v_permlane16_swap+v_permlane32_swap instead of two ds_bpermute round trips (loads drained first); on top of hb store widening
# baseline (speedup 1.0000x reference)
;   DI void operator()(LAS unsigned char* lds, f32x4 (&acc)[2][2][4][2], int pm, int pn, int wr, int wc, int fr, int fq) const {
;     ...
;       for (int m = mb; m < mb + 2; ++m) {
;         const int s = s0 + ai * HALF + m * 16;
;         f32x4 v[2][2];
; #pragma unroll
;         for (int bj = 0; bj < 2; ++bj)
; #pragma unroll
;           for (int n = 0; n < 2; ++n) v[bj][n] = acc[ai][bj][m][n] * rstd[ai][m];
;         if (type < 2) {
;           float q = 0.f;
; #pragma unroll
;           for (int bj = 0; bj < 2; ++bj)
; #pragma unroll
;             for (int n = 0; n < 2; ++n) q += v[bj][n][0] * v[bj][n][0] + v[bj][n][1] * v[bj][n][1] + v[bj][n][2] * v[bj][n][2] + v[bj][n][3] * v[bj][n][3];
;           q += __shfl_xor(q, 16); q += __shfl_xor(q, 32);
;           float rn = rsqrtf(q * (1.0f / 64.0f) + EPS);
;           if (type == 0) rn *= 0.125f * LOG2E;
; #pragma unroll
;           for (int n = 0; n < 2; ++n) {
;             const f32x4 x1 = v[0][n] * g1[n] * rn, x2 = v[1][n] * g2[n] * rn;
;             v[0][n] = x1 * cs[m][n] - x2 * sn[m][n]; v[1][n] = x2 * cs[m][n] + x1 * sn[m][n];
;           }
.LBB0_470:
	s_waitcnt lgkmcnt(0)
	v_pk_mul_f32 v[124:125], v[124:125], v[188:189] op_sel_hi:[1,0]
	v_pk_mul_f32 v[190:191], v[122:123], v[188:189] op_sel_hi:[1,0]
	v_pk_mul_f32 v[100:101], v[100:101], v[188:189] op_sel_hi:[1,0]
	v_pk_mul_f32 v[192:193], v[98:99], v[188:189] op_sel_hi:[1,0]
	v_pk_mul_f32 v[98:99], v[140:141], v[188:189] op_sel_hi:[1,0]
	v_pk_mul_f32 v[138:139], v[138:139], v[188:189] op_sel_hi:[1,0]
	v_pk_mul_f32 v[122:123], v[128:129], v[188:189] op_sel_hi:[1,0]
	s_and_b64 vcc, exec, s[44:45]
	v_pk_mul_f32 v[126:127], v[126:127], v[188:189] op_sel_hi:[1,0]
	s_cbranch_vccnz .LBB0_472
	v_mov_b32_e32 v140, v191
	v_mov_b32_e32 v141, v193
	v_mov_b32_e32 v128, v190
	v_mov_b32_e32 v129, v192
	v_pk_mul_f32 v[140:141], v[140:141], v[140:141]
	v_mov_b32_e32 v180, v127
	v_pk_fma_f32 v[128:129], v[128:129], v[128:129], v[140:141]
	v_mov_b32_e32 v140, v124
	v_mov_b32_e32 v141, v100
	v_pk_fma_f32 v[128:129], v[140:141], v[140:141], v[128:129]
	v_mov_b32_e32 v140, v125
	v_mov_b32_e32 v141, v101
	v_mov_b32_e32 v181, v139
	v_pk_fma_f32 v[128:129], v[140:141], v[140:141], v[128:129]
	v_mov_b32_e32 v140, v126
	v_mov_b32_e32 v141, v138
	v_pk_mul_f32 v[180:181], v[180:181], v[180:181]
	v_add_f32_e32 v128, v128, v129
	v_pk_fma_f32 v[140:141], v[140:141], v[140:141], v[180:181]
	v_mov_b32_e32 v180, v122
	v_mov_b32_e32 v181, v98
	v_pk_fma_f32 v[140:141], v[180:181], v[180:181], v[140:141]
	v_mov_b32_e32 v180, v123
	v_mov_b32_e32 v181, v99
	v_pk_fma_f32 v[140:141], v[180:181], v[180:181], v[140:141]
	v_xor_b32_e32 v129, 16, v224
	v_add_f32_e32 v128, v141, v128
	v_add_f32_e32 v128, v140, v128
	v_and_b32_e32 v140, 64, v224
	v_add_u32_e32 v140, 64, v140
	v_cmp_lt_i32_e32 vcc, v129, v140
	v_pk_mul_f32 v[124:125], v[124:125], v[16:17]
	v_pk_mul_f32 v[98:99], v[98:99], v[12:13]
	v_cndmask_b32_e32 v129, v224, v129, vcc
	v_lshlrev_b32_e32 v129, 2, v129
	s_waitcnt vmcnt(0) lgkmcnt(0)
	v_mov_b32_e32 v129, v128
	s_nop 1
	v_permlane16_swap_b32_e32 v128, v129
	v_pk_mul_f32 v[100:101], v[100:101], v[8:9]
	s_waitcnt lgkmcnt(0)
	v_add_f32_e32 v128, v128, v129
	v_xor_b32_e32 v129, 32, v224
	v_cmp_lt_i32_e32 vcc, v129, v140
	v_pk_mul_f32 v[140:141], v[190:191], v[14:15]
	s_nop 0
	v_cndmask_b32_e32 v129, v224, v129, vcc
	v_lshlrev_b32_e32 v129, 2, v129
	v_mov_b32_e32 v129, v128
	s_nop 1
	v_permlane32_swap_b32_e32 v128, v129
	s_waitcnt lgkmcnt(0)
	v_add_f32_e32 v128, v128, v129
	v_fmamk_f32 v128, v128, 0x3c800000, v227
	v_mul_f32_e32 v129, 0x4b800000, v128
	v_cmp_gt_f32_e32 vcc, s16, v128
	s_nop 1
	v_cndmask_b32_e32 v128, v128, v129, vcc
	v_rsq_f32_e32 v128, v128
	s_nop 0
	v_mul_f32_e32 v129, 0x45800000, v128
	v_cndmask_b32_e32 v128, v128, v129, vcc
	v_mul_f32_e32 v129, 0x3e38aa3b, v128
	v_cndmask_b32_e64 v128, v128, v129, s[96:97]
	v_pk_mul_f32 v[180:181], v[124:125], v[128:129] op_sel_hi:[1,0]
	v_pk_mul_f32 v[124:125], v[138:139], v[10:11]
	v_pk_mul_f32 v[98:99], v[98:99], v[128:129] op_sel_hi:[1,0]
	v_pk_mul_f32 v[138:139], v[124:125], v[128:129] op_sel_hi:[1,0]
	v_pk_mul_f32 v[140:141], v[140:141], v[128:129] op_sel_hi:[1,0]
	v_pk_mul_f32 v[182:183], v[142:143], v[138:139]
	v_pk_mul_f32 v[124:125], v[144:145], v[98:99]
	v_pk_fma_f32 v[190:191], v[134:135], v[140:141], v[182:183] neg_lo:[0,0,1] neg_hi:[0,0,1]
	v_pk_fma_f32 v[124:125], v[136:137], v[180:181], v[124:125] neg_lo:[0,0,1] neg_hi:[0,0,1]
	v_pk_mul_f32 v[140:141], v[142:143], v[140:141]
	v_pk_mul_f32 v[180:181], v[144:145], v[180:181]
	v_pk_fma_f32 v[138:139], v[134:135], v[138:139], v[140:141]
	v_pk_fma_f32 v[98:99], v[136:137], v[98:99], v[180:181]
	v_pk_mul_f32 v[140:141], v[192:193], v[6:7]
	v_pk_mul_f32 v[180:181], v[100:101], v[128:129] op_sel_hi:[1,0]
	v_pk_mul_f32 v[100:101], v[122:123], v[4:5]
	v_pk_mul_f32 v[122:123], v[126:127], v[2:3]
	v_pk_mul_f32 v[140:141], v[140:141], v[128:129] op_sel_hi:[1,0]
	v_pk_mul_f32 v[126:127], v[100:101], v[128:129] op_sel_hi:[1,0]
	v_pk_mul_f32 v[128:129], v[122:123], v[128:129] op_sel_hi:[1,0]
	v_pk_mul_f32 v[100:101], v[132:133], v[126:127]
	v_pk_mul_f32 v[122:123], v[130:131], v[128:129]
	v_pk_fma_f32 v[100:101], v[116:117], v[180:181], v[100:101] neg_lo:[0,0,1] neg_hi:[0,0,1]
	v_pk_fma_f32 v[192:193], v[114:115], v[140:141], v[122:123] neg_lo:[0,0,1] neg_hi:[0,0,1]
	v_pk_mul_f32 v[140:141], v[130:131], v[140:141]
	v_pk_mul_f32 v[122:123], v[132:133], v[180:181]
	s_nop 0
	v_pk_fma_f32 v[122:123], v[116:117], v[126:127], v[122:123]
	v_pk_fma_f32 v[126:127], v[114:115], v[128:129], v[140:141]
;   DI void operator()(LAS unsigned char* lds, f32x4 (&acc)[2][2][4][2], int pm, int pn, int wr, int wc, int fr, int fq) const {
;     const int g = pn / 12, type = (pn % 12) >> 2, head = (pn & 3) * 4 + wc;
;     bf16_t* base = qkv + (size_t)((g * 3 + type) * 16 + head) * S_LEN * 64;
;     const float* gp = (type == 0 ? qg : kg) + g * 64;
;     const int s0 = pm * BM + wr * 64 + fr;
;     float rstd[2][4];
; #pragma unroll
;     for (int ai = 0; ai < 2; ++ai)
; #pragma unroll
;       for (int m = 0; m < 4; ++m) rstd[ai][m] = ((const LAS float*)(lds + 135168))[ai * HALF + wr * 64 + m * 16 + fr];
;     f32x4 g1[2], g2[2];
;     if (type < 2) {
; #pragma unroll
;       for (int n = 0; n < 2; ++n) { g1[n] = *(const LAS f32x4*)(lds + EQ_GN + (8 * fq + 4 * n) * 4); g2[n] = *(const LAS f32x4*)(lds + EQ_GN + (32 + 8 * fq + 4 * n) * 4); }
;     }
; #pragma unroll
;     for (int aim = 0; aim < 4; ++aim) {
;       const int ai = aim >> 1, mb = (aim & 1) * 2;
;       f32x4 cs[4][2], sn[4][2];
;       if (type < 2) {
; #pragma unroll
;         for (int m = mb; m < mb + 2; ++m)
; #pragma unroll
;           for (int n = 0; n < 2; ++n) {
;             if (aim == 0) {
;               const int tr = wr * 32 + m * 16 + fr;
;               cs[m][n] = *(const LAS f32x4*)(lds + EQ_CS + tr * EQ_CSS + (8 * fq + 4 * n) * 4);
;               sn[m][n] = *(const LAS f32x4*)(lds + EQ_CS + tr * EQ_CSS + 128 + (8 * fq + 4 * n) * 4);
;             } else {
;               const size_t o = (size_t)(s0 + ai * HALF + m * 16) * 32 + 8 * fq + 4 * n;
;               cs[m][n] = *(const f32x4*)(cosT + o); sn[m][n] = *(const f32x4*)(sinT + o);
;             }
;           }
;       }
;       EPI_FENCE;
; #pragma unroll
;       for (int m = mb; m < mb + 2; ++m) {
;         const int s = s0 + ai * HALF + m * 16;
;         f32x4 v[2][2];
; #pragma unroll
;         for (int bj = 0; bj < 2; ++bj)
; #pragma unroll
;           for (int n = 0; n < 2; ++n) v[bj][n] = acc[ai][bj][m][n] * rstd[ai][m];
;         if (type < 2) {
;           float q = 0.f;
; #pragma unroll
;           for (int bj = 0; bj < 2; ++bj)
; #pragma unroll
;             for (int n = 0; n < 2; ++n) q += v[bj][n][0] * v[bj][n][0] + v[bj][n][1] * v[bj][n][1] + v[bj][n][2] * v[bj][n][2] + v[bj][n][3] * v[bj][n][3];
;           q += __shfl_xor(q, 16); q += __shfl_xor(q, 32);
;           float rn = rsqrtf(q * (1.0f / 64.0f) + EPS);
.LBB0_472:
	s_mul_i32 s21, s21, 3
	s_lshl_b32 s20, s20, 2
	s_add_i32 s21, s21, s19
	s_and_b32 s20, s20, 12
	s_lshl_b32 s19, s21, 4
	s_or_b32 s19, s19, s20
	v_or_b32_e32 v128, s19, v229
	v_ashrrev_i32_e32 v129, 31, v128
	v_lshlrev_b64 v[128:129], 21, v[128:129]
	v_lshl_add_u64 v[128:129], s[30:31], 0, v[128:129]
	v_lshl_add_u64 v[180:181], v[128:129], 0, v[0:1]
	v_add_u32_e32 v0, s18, v228
	v_or_b32_e32 v182, v0, v219
	v_ashrrev_i32_e32 v183, 31, v182
	v_lshlrev_b64 v[128:129], 7, v[182:183]
	v_mov_b32_e32 v0, v189
	v_lshl_add_u64 v[128:129], v[180:181], 0, v[128:129]
	v_cvt_pk_bf16_f32 v190, v190, v191
	v_cvt_pk_bf16_f32 v191, v124, v125
	v_cvt_pk_bf16_f32 v192, v192, v193
	v_cvt_pk_bf16_f32 v193, v100, v101
	v_cvt_pk_bf16_f32 v125, v98, v99
	v_pk_mul_f32 v[80:81], v[80:81], v[0:1] op_sel_hi:[1,0]
	v_pk_mul_f32 v[98:99], v[78:79], v[0:1] op_sel_hi:[1,0]
	v_pk_mul_f32 v[68:69], v[68:69], v[0:1] op_sel_hi:[1,0]
	v_pk_mul_f32 v[100:101], v[66:67], v[0:1] op_sel_hi:[1,0]
	v_pk_mul_f32 v[66:67], v[96:97], v[0:1] op_sel_hi:[1,0]
	v_pk_mul_f32 v[94:95], v[94:95], v[0:1] op_sel_hi:[1,0]
	v_pk_mul_f32 v[78:79], v[88:89], v[0:1] op_sel_hi:[1,0]
	s_and_b64 vcc, exec, s[44:45]
	v_pk_mul_f32 v[86:87], v[86:87], v[0:1] op_sel_hi:[1,0]
	global_store_dwordx4 v[128:129], v[190:193], off
	v_cvt_pk_bf16_f32 v124, v138, v139
	v_cvt_pk_bf16_f32 v126, v126, v127
	v_cvt_pk_bf16_f32 v127, v122, v123
	global_store_dwordx4 v[128:129], v[124:127], off offset:64
	s_cbranch_vccnz .LBB0_474
	v_mov_b32_e32 v96, v99
	v_mov_b32_e32 v97, v101
	v_mov_b32_e32 v88, v98
	v_mov_b32_e32 v89, v100
	v_pk_mul_f32 v[96:97], v[96:97], v[96:97]
	v_mov_b32_e32 v122, v87
	v_pk_fma_f32 v[88:89], v[88:89], v[88:89], v[96:97]
	v_mov_b32_e32 v96, v80
	v_mov_b32_e32 v97, v68
	v_pk_fma_f32 v[88:89], v[96:97], v[96:97], v[88:89]
	v_mov_b32_e32 v96, v81
	v_mov_b32_e32 v97, v69
	v_mov_b32_e32 v123, v95
	v_pk_fma_f32 v[88:89], v[96:97], v[96:97], v[88:89]
	v_mov_b32_e32 v96, v86
	v_mov_b32_e32 v97, v94
	v_pk_mul_f32 v[122:123], v[122:123], v[122:123]
	v_add_f32_e32 v0, v88, v89
	v_pk_fma_f32 v[96:97], v[96:97], v[96:97], v[122:123]
	v_mov_b32_e32 v122, v78
	v_mov_b32_e32 v123, v66
	v_and_b32_e32 v89, 64, v224
	v_pk_fma_f32 v[96:97], v[122:123], v[122:123], v[96:97]
	v_mov_b32_e32 v122, v79
	v_mov_b32_e32 v123, v67
	v_xor_b32_e32 v88, 16, v224
	v_add_u32_e32 v89, 64, v89
	v_pk_fma_f32 v[96:97], v[122:123], v[122:123], v[96:97]
	v_cmp_lt_i32_e32 vcc, v88, v89
	v_add_f32_e32 v0, v97, v0
	v_add_f32_e32 v0, v96, v0
	v_cndmask_b32_e32 v88, v224, v88, vcc
	v_lshlrev_b32_e32 v88, 2, v88
	s_waitcnt vmcnt(0) lgkmcnt(0)
	v_mov_b32_e32 v88, v0
	s_nop 1
	v_permlane16_swap_b32_e32 v0, v88
	v_pk_mul_f32 v[80:81], v[80:81], v[16:17]
	v_pk_mul_f32 v[66:67], v[66:67], v[12:13]
	v_pk_mul_f32 v[68:69], v[68:69], v[8:9]
	s_waitcnt lgkmcnt(0)
	v_add_f32_e32 v0, v0, v88
	v_xor_b32_e32 v88, 32, v224
	v_cmp_lt_i32_e32 vcc, v88, v89
	s_nop 1
	v_cndmask_b32_e32 v88, v224, v88, vcc
	v_lshlrev_b32_e32 v88, 2, v88
	v_mov_b32_e32 v88, v0
	s_nop 1
	v_permlane32_swap_b32_e32 v0, v88
	s_waitcnt lgkmcnt(0)
	v_add_f32_e32 v0, v0, v88
	v_fmamk_f32 v0, v0, 0x3c800000, v227
	v_mul_f32_e32 v88, 0x4b800000, v0
	v_cmp_gt_f32_e32 vcc, s16, v0
	s_nop 1
	v_cndmask_b32_e32 v0, v0, v88, vcc
	v_rsq_f32_e32 v0, v0
	s_nop 0
	v_mul_f32_e32 v88, 0x45800000, v0
	v_cndmask_b32_e32 v0, v0, v88, vcc
	v_mul_f32_e32 v88, 0x3e38aa3b, v0
	v_cndmask_b32_e64 v0, v0, v88, s[96:97]
	v_pk_mul_f32 v[96:97], v[80:81], v[0:1] op_sel_hi:[1,0]
	v_pk_mul_f32 v[80:81], v[94:95], v[10:11]
	v_pk_mul_f32 v[66:67], v[66:67], v[0:1] op_sel_hi:[1,0]
	v_pk_mul_f32 v[88:89], v[98:99], v[14:15]
	v_pk_mul_f32 v[94:95], v[80:81], v[0:1] op_sel_hi:[1,0]
	v_pk_mul_f32 v[80:81], v[92:93], v[66:67]
	v_pk_mul_f32 v[88:89], v[88:89], v[0:1] op_sel_hi:[1,0]
	v_pk_mul_f32 v[98:99], v[90:91], v[94:95]
	v_pk_fma_f32 v[80:81], v[84:85], v[96:97], v[80:81] neg_lo:[0,0,1] neg_hi:[0,0,1]
	v_pk_mul_f32 v[96:97], v[92:93], v[96:97]
	v_pk_fma_f32 v[98:99], v[82:83], v[88:89], v[98:99] neg_lo:[0,0,1] neg_hi:[0,0,1]
	v_pk_mul_f32 v[88:89], v[90:91], v[88:89]
	v_pk_fma_f32 v[66:67], v[84:85], v[66:67], v[96:97]
	v_pk_mul_f32 v[96:97], v[68:69], v[0:1] op_sel_hi:[1,0]
	v_pk_mul_f32 v[68:69], v[78:79], v[4:5]
	v_pk_mul_f32 v[78:79], v[86:87], v[2:3]
	v_pk_fma_f32 v[94:95], v[82:83], v[94:95], v[88:89]
	v_pk_mul_f32 v[88:89], v[100:101], v[6:7]
	v_pk_mul_f32 v[122:123], v[78:79], v[0:1] op_sel_hi:[1,0]
	v_pk_mul_f32 v[88:89], v[88:89], v[0:1] op_sel_hi:[1,0]
	v_pk_mul_f32 v[86:87], v[68:69], v[0:1] op_sel_hi:[1,0]
	v_pk_mul_f32 v[78:79], v[74:75], v[122:123]
	v_pk_mul_f32 v[68:69], v[76:77], v[86:87]
	v_pk_fma_f32 v[100:101], v[70:71], v[88:89], v[78:79] neg_lo:[0,0,1] neg_hi:[0,0,1]
	v_pk_mul_f32 v[88:89], v[74:75], v[88:89]
	v_pk_mul_f32 v[78:79], v[76:77], v[96:97]
	v_pk_fma_f32 v[68:69], v[72:73], v[96:97], v[68:69] neg_lo:[0,0,1] neg_hi:[0,0,1]
	v_pk_fma_f32 v[78:79], v[72:73], v[86:87], v[78:79]
	v_pk_fma_f32 v[86:87], v[70:71], v[122:123], v[88:89]

;   DI void operator()(LAS unsigned char* lds, f32x4 (&acc)[2][2][4][2], int pm, int pn, int wr, int wc, int fr, int fq) const {
;     ...
;       for (int m = mb; m < mb + 2; ++m) {
;         const int s = s0 + ai * HALF + m * 16;
;         f32x4 v[2][2];
; #pragma unroll
;         for (int bj = 0; bj < 2; ++bj)
; #pragma unroll
;           for (int n = 0; n < 2; ++n) v[bj][n] = acc[ai][bj][m][n] * rstd[ai][m];
;         if (type < 2) {
;           float q = 0.f;
; #pragma unroll
;           for (int bj = 0; bj < 2; ++bj)
; #pragma unroll
;             for (int n = 0; n < 2; ++n) q += v[bj][n][0] * v[bj][n][0] + v[bj][n][1] * v[bj][n][1] + v[bj][n][2] * v[bj][n][2] + v[bj][n][3] * v[bj][n][3];
;           q += __shfl_xor(q, 16); q += __shfl_xor(q, 32);
;           float rn = rsqrtf(q * (1.0f / 64.0f) + EPS);
;           if (type == 0) rn *= 0.125f * LOG2E;
; #pragma unroll
;           for (int n = 0; n < 2; ++n) {
;             const f32x4 x1 = v[0][n] * g1[n] * rn, x2 = v[1][n] * g2[n] * rn;
;             v[0][n] = x1 * cs[m][n] - x2 * sn[m][n]; v[1][n] = x2 * cs[m][n] + x1 * sn[m][n];
;           }
.LBB0_476:
	v_pk_mul_f32 v[168:169], v[168:169], v[186:187] op_sel_hi:[1,0]
	v_pk_mul_f32 v[192:193], v[166:167], v[186:187] op_sel_hi:[1,0]
	v_pk_mul_f32 v[164:165], v[164:165], v[186:187] op_sel_hi:[1,0]
	v_pk_mul_f32 v[194:195], v[162:163], v[186:187] op_sel_hi:[1,0]
	v_pk_mul_f32 v[162:163], v[176:177], v[186:187] op_sel_hi:[1,0]
	v_pk_mul_f32 v[174:175], v[174:175], v[186:187] op_sel_hi:[1,0]
	v_pk_mul_f32 v[166:167], v[172:173], v[186:187] op_sel_hi:[1,0]
	s_and_b64 vcc, exec, s[44:45]
	v_pk_mul_f32 v[170:171], v[170:171], v[186:187] op_sel_hi:[1,0]
	s_cbranch_vccnz .LBB0_478
	v_mov_b32_e32 v176, v193
	v_mov_b32_e32 v177, v195
	v_mov_b32_e32 v172, v192
	v_mov_b32_e32 v173, v194
	v_pk_mul_f32 v[176:177], v[176:177], v[176:177]
	v_mov_b32_e32 v196, v171
	v_pk_fma_f32 v[172:173], v[172:173], v[172:173], v[176:177]
	v_mov_b32_e32 v176, v168
	v_mov_b32_e32 v177, v164
	v_pk_fma_f32 v[172:173], v[176:177], v[176:177], v[172:173]
	v_mov_b32_e32 v176, v169
	v_mov_b32_e32 v177, v165
	v_mov_b32_e32 v197, v175
	v_pk_fma_f32 v[172:173], v[176:177], v[176:177], v[172:173]
	v_mov_b32_e32 v176, v170
	v_mov_b32_e32 v177, v174
	v_pk_mul_f32 v[196:197], v[196:197], v[196:197]
	v_add_f32_e32 v172, v172, v173
	v_pk_fma_f32 v[176:177], v[176:177], v[176:177], v[196:197]
	v_mov_b32_e32 v196, v166
	v_mov_b32_e32 v197, v162
	v_pk_fma_f32 v[176:177], v[196:197], v[196:197], v[176:177]
	v_mov_b32_e32 v196, v167
	v_mov_b32_e32 v197, v163
	v_pk_fma_f32 v[176:177], v[196:197], v[196:197], v[176:177]
	v_xor_b32_e32 v173, 16, v224
	v_add_f32_e32 v172, v177, v172
	v_add_f32_e32 v172, v176, v172
	v_and_b32_e32 v176, 64, v224
	v_add_u32_e32 v176, 64, v176
	v_cmp_lt_i32_e32 vcc, v173, v176
	v_pk_mul_f32 v[168:169], v[168:169], v[16:17]
	v_pk_mul_f32 v[162:163], v[162:163], v[12:13]
	v_cndmask_b32_e32 v173, v224, v173, vcc
	v_lshlrev_b32_e32 v173, 2, v173
	s_waitcnt vmcnt(0) lgkmcnt(0)
	v_mov_b32_e32 v173, v172
	s_nop 1
	v_permlane16_swap_b32_e32 v172, v173
	v_pk_mul_f32 v[164:165], v[164:165], v[8:9]
	s_waitcnt lgkmcnt(0)
	v_add_f32_e32 v172, v172, v173
	v_xor_b32_e32 v173, 32, v224
	v_cmp_lt_i32_e32 vcc, v173, v176
	v_pk_mul_f32 v[176:177], v[192:193], v[14:15]
	s_nop 0
	v_cndmask_b32_e32 v173, v224, v173, vcc
	v_lshlrev_b32_e32 v173, 2, v173
	v_mov_b32_e32 v173, v172
	s_nop 1
	v_permlane32_swap_b32_e32 v172, v173
	s_waitcnt lgkmcnt(0)
	v_add_f32_e32 v172, v172, v173
	v_fmamk_f32 v172, v172, 0x3c800000, v227
	v_mul_f32_e32 v173, 0x4b800000, v172
	v_cmp_gt_f32_e32 vcc, s16, v172
	s_nop 1
	v_cndmask_b32_e32 v172, v172, v173, vcc
	v_rsq_f32_e32 v172, v172
	s_nop 0
	v_mul_f32_e32 v173, 0x45800000, v172
	v_cndmask_b32_e32 v172, v172, v173, vcc
	v_mul_f32_e32 v173, 0x3e38aa3b, v172
	v_cndmask_b32_e64 v172, v172, v173, s[96:97]
	v_pk_mul_f32 v[196:197], v[168:169], v[172:173] op_sel_hi:[1,0]
	v_pk_mul_f32 v[168:169], v[174:175], v[10:11]
	v_pk_mul_f32 v[162:163], v[162:163], v[172:173] op_sel_hi:[1,0]
	v_pk_mul_f32 v[174:175], v[168:169], v[172:173] op_sel_hi:[1,0]
	v_pk_mul_f32 v[176:177], v[176:177], v[172:173] op_sel_hi:[1,0]
	s_waitcnt vmcnt(0)
	v_pk_mul_f32 v[192:193], v[138:139], v[174:175]
	v_pk_mul_f32 v[168:169], v[140:141], v[162:163]
	v_pk_fma_f32 v[192:193], v[126:127], v[176:177], v[192:193] neg_lo:[0,0,1] neg_hi:[0,0,1]
	v_pk_fma_f32 v[168:169], v[128:129], v[196:197], v[168:169] neg_lo:[0,0,1] neg_hi:[0,0,1]
	v_pk_mul_f32 v[176:177], v[138:139], v[176:177]
	v_pk_mul_f32 v[196:197], v[140:141], v[196:197]
	v_pk_fma_f32 v[174:175], v[126:127], v[174:175], v[176:177]
	v_pk_fma_f32 v[162:163], v[128:129], v[162:163], v[196:197]
	v_pk_mul_f32 v[176:177], v[194:195], v[6:7]
	v_pk_mul_f32 v[196:197], v[164:165], v[172:173] op_sel_hi:[1,0]
	v_pk_mul_f32 v[164:165], v[166:167], v[4:5]
	v_pk_mul_f32 v[166:167], v[170:171], v[2:3]
	v_pk_mul_f32 v[176:177], v[176:177], v[172:173] op_sel_hi:[1,0]
	v_pk_mul_f32 v[170:171], v[164:165], v[172:173] op_sel_hi:[1,0]
	v_pk_mul_f32 v[172:173], v[166:167], v[172:173] op_sel_hi:[1,0]
	v_pk_mul_f32 v[164:165], v[124:125], v[170:171]
	v_pk_mul_f32 v[166:167], v[122:123], v[172:173]
	v_pk_fma_f32 v[164:165], v[100:101], v[196:197], v[164:165] neg_lo:[0,0,1] neg_hi:[0,0,1]
	v_pk_fma_f32 v[194:195], v[98:99], v[176:177], v[166:167] neg_lo:[0,0,1] neg_hi:[0,0,1]
	v_pk_mul_f32 v[176:177], v[122:123], v[176:177]
	v_pk_mul_f32 v[166:167], v[124:125], v[196:197]
	s_nop 0
	v_pk_fma_f32 v[166:167], v[100:101], v[170:171], v[166:167]
	v_pk_fma_f32 v[170:171], v[98:99], v[172:173], v[176:177]
; DI unsigned cvt_pk(float lo, float hi) { unsigned r; asm("v_cvt_pk_bf16_f32 %0, %1, %2" : "=v"(r) : "v"(lo), "v"(hi)); return r; }
;   DI void operator()(LAS unsigned char* lds, f32x4 (&acc)[2][2][4][2], int pm, int pn, int wr, int wc, int fr, int fq) const {
;     ...
;         const int s = s0 + ai * HALF + m * 16;
;         f32x4 v[2][2];
; #pragma unroll
;         for (int bj = 0; bj < 2; ++bj)
; #pragma unroll
;           for (int n = 0; n < 2; ++n) v[bj][n] = acc[ai][bj][m][n] * rstd[ai][m];
;         if (type < 2) {
;           float q = 0.f;
; #pragma unroll
;           for (int bj = 0; bj < 2; ++bj)
; #pragma unroll
;             for (int n = 0; n < 2; ++n) q += v[bj][n][0] * v[bj][n][0] + v[bj][n][1] * v[bj][n][1] + v[bj][n][2] * v[bj][n][2] + v[bj][n][3] * v[bj][n][3];
;           q += __shfl_xor(q, 16); q += __shfl_xor(q, 32);
;           float rn = rsqrtf(q * (1.0f / 64.0f) + EPS);
;           if (type == 0) rn *= 0.125f * LOG2E;
; #pragma unroll
;           for (int n = 0; n < 2; ++n) {
;             const f32x4 x1 = v[0][n] * g1[n] * rn, x2 = v[1][n] * g2[n] * rn;
;             v[0][n] = x1 * cs[m][n] - x2 * sn[m][n]; v[1][n] = x2 * cs[m][n] + x1 * sn[m][n];
;           }
;         }
;         bf16_t* rp = base + (size_t)s * 64 + 8 * fq;
; #pragma unroll
;         for (int bj = 0; bj < 2; ++bj) {
;           u32x4 w; w.x = cvt_pk(v[bj][0][0], v[bj][0][1]); w.y = cvt_pk(v[bj][0][2], v[bj][0][3]); w.z = cvt_pk(v[bj][1][0], v[bj][1][1]); w.w = cvt_pk(v[bj][1][2], v[bj][1][3]);
;           *(u32x4*)(rp + bj * 32) = w;
.LBB0_478:
	v_lshlrev_b64 v[172:173], 7, v[190:191]
	v_cvt_pk_bf16_f32 v170, v170, v171
	v_cvt_pk_bf16_f32 v171, v166, v167
	v_mov_b32_e32 v166, v187
	v_lshl_add_u64 v[172:173], v[180:181], 0, v[172:173]
	v_cvt_pk_bf16_f32 v190, v192, v193
	v_cvt_pk_bf16_f32 v191, v168, v169
	v_cvt_pk_bf16_f32 v193, v164, v165
	v_cvt_pk_bf16_f32 v169, v162, v163
	v_pk_mul_f32 v[152:153], v[152:153], v[166:167] op_sel_hi:[1,0]
	v_pk_mul_f32 v[162:163], v[150:151], v[166:167] op_sel_hi:[1,0]
	v_pk_mul_f32 v[148:149], v[148:149], v[166:167] op_sel_hi:[1,0]
	v_pk_mul_f32 v[164:165], v[146:147], v[166:167] op_sel_hi:[1,0]
	v_pk_mul_f32 v[146:147], v[160:161], v[166:167] op_sel_hi:[1,0]
	v_pk_mul_f32 v[158:159], v[158:159], v[166:167] op_sel_hi:[1,0]
	v_pk_mul_f32 v[150:151], v[156:157], v[166:167] op_sel_hi:[1,0]
	s_and_b64 vcc, exec, s[44:45]
	v_pk_mul_f32 v[154:155], v[154:155], v[166:167] op_sel_hi:[1,0]
	v_cvt_pk_bf16_f32 v192, v194, v195
	global_store_dwordx4 v[172:173], v[190:193], off
	v_cvt_pk_bf16_f32 v168, v174, v175
	global_store_dwordx4 v[172:173], v[168:171], off offset:64
	s_cbranch_vccnz .LBB0_480
	v_mov_b32_e32 v160, v163
	v_mov_b32_e32 v161, v165
	v_mov_b32_e32 v156, v162
	v_mov_b32_e32 v157, v164
	v_pk_mul_f32 v[160:161], v[160:161], v[160:161]
	v_mov_b32_e32 v166, v155
	v_pk_fma_f32 v[156:157], v[156:157], v[156:157], v[160:161]
	v_mov_b32_e32 v160, v152
	v_mov_b32_e32 v161, v148
	v_pk_fma_f32 v[156:157], v[160:161], v[160:161], v[156:157]
	v_mov_b32_e32 v160, v153
	v_mov_b32_e32 v161, v149
	v_mov_b32_e32 v167, v159
	v_pk_fma_f32 v[156:157], v[160:161], v[160:161], v[156:157]
	v_mov_b32_e32 v160, v154
	v_mov_b32_e32 v161, v158
	v_pk_mul_f32 v[166:167], v[166:167], v[166:167]
	v_add_f32_e32 v156, v156, v157
	v_pk_fma_f32 v[160:161], v[160:161], v[160:161], v[166:167]
	v_mov_b32_e32 v166, v150
	v_mov_b32_e32 v167, v146
	v_pk_fma_f32 v[160:161], v[166:167], v[166:167], v[160:161]
	v_mov_b32_e32 v166, v151
	v_mov_b32_e32 v167, v147
	v_pk_fma_f32 v[160:161], v[166:167], v[166:167], v[160:161]
	v_xor_b32_e32 v157, 16, v224
	v_add_f32_e32 v156, v161, v156
	v_add_f32_e32 v156, v160, v156
	v_and_b32_e32 v160, 64, v224
	v_add_u32_e32 v160, 64, v160
	v_cmp_lt_i32_e32 vcc, v157, v160
	v_pk_mul_f32 v[152:153], v[152:153], v[16:17]
	v_pk_mul_f32 v[146:147], v[146:147], v[12:13]
	v_cndmask_b32_e32 v157, v224, v157, vcc
	v_lshlrev_b32_e32 v157, 2, v157
	s_waitcnt vmcnt(0) lgkmcnt(0)
	v_mov_b32_e32 v157, v156
	s_nop 1
	v_permlane16_swap_b32_e32 v156, v157
	v_pk_mul_f32 v[148:149], v[148:149], v[8:9]
	s_waitcnt lgkmcnt(0)
	v_add_f32_e32 v156, v156, v157
	v_xor_b32_e32 v157, 32, v224
	v_cmp_lt_i32_e32 vcc, v157, v160
	v_pk_mul_f32 v[160:161], v[162:163], v[14:15]
	s_nop 0
	v_cndmask_b32_e32 v157, v224, v157, vcc
	v_lshlrev_b32_e32 v157, 2, v157
	v_mov_b32_e32 v157, v156
	s_nop 1
	v_permlane32_swap_b32_e32 v156, v157
	s_waitcnt lgkmcnt(0)
	v_add_f32_e32 v156, v156, v157
	v_fmamk_f32 v156, v156, 0x3c800000, v227
	v_mul_f32_e32 v157, 0x4b800000, v156
	v_cmp_gt_f32_e32 vcc, s16, v156
	s_nop 1
	v_cndmask_b32_e32 v156, v156, v157, vcc
	v_rsq_f32_e32 v156, v156
	s_nop 0
	v_mul_f32_e32 v157, 0x45800000, v156
	v_cndmask_b32_e32 v156, v156, v157, vcc
	v_mul_f32_e32 v157, 0x3e38aa3b, v156
	v_cndmask_b32_e64 v156, v156, v157, s[96:97]
	v_pk_mul_f32 v[166:167], v[152:153], v[156:157] op_sel_hi:[1,0]
	v_pk_mul_f32 v[152:153], v[158:159], v[10:11]
	v_pk_mul_f32 v[146:147], v[146:147], v[156:157] op_sel_hi:[1,0]
	v_pk_mul_f32 v[158:159], v[152:153], v[156:157] op_sel_hi:[1,0]
	v_pk_mul_f32 v[160:161], v[160:161], v[156:157] op_sel_hi:[1,0]
	s_waitcnt vmcnt(0)
	v_pk_mul_f32 v[162:163], v[94:95], v[158:159]
	v_pk_mul_f32 v[152:153], v[96:97], v[146:147]
	v_pk_fma_f32 v[162:163], v[86:87], v[160:161], v[162:163] neg_lo:[0,0,1] neg_hi:[0,0,1]
	v_pk_fma_f32 v[152:153], v[88:89], v[166:167], v[152:153] neg_lo:[0,0,1] neg_hi:[0,0,1]
	v_pk_mul_f32 v[160:161], v[94:95], v[160:161]
	v_pk_mul_f32 v[166:167], v[96:97], v[166:167]
	v_pk_fma_f32 v[158:159], v[86:87], v[158:159], v[160:161]
	v_pk_fma_f32 v[146:147], v[88:89], v[146:147], v[166:167]
	v_pk_mul_f32 v[160:161], v[164:165], v[6:7]
	v_pk_mul_f32 v[166:167], v[148:149], v[156:157] op_sel_hi:[1,0]
	v_pk_mul_f32 v[148:149], v[150:151], v[4:5]
	v_pk_mul_f32 v[150:151], v[154:155], v[2:3]
	v_pk_mul_f32 v[160:161], v[160:161], v[156:157] op_sel_hi:[1,0]
	v_pk_mul_f32 v[154:155], v[148:149], v[156:157] op_sel_hi:[1,0]
	v_pk_mul_f32 v[156:157], v[150:151], v[156:157] op_sel_hi:[1,0]
	v_pk_mul_f32 v[148:149], v[80:81], v[154:155]
	v_pk_mul_f32 v[150:151], v[78:79], v[156:157]
	v_pk_fma_f32 v[148:149], v[68:69], v[166:167], v[148:149] neg_lo:[0,0,1] neg_hi:[0,0,1]
	v_pk_fma_f32 v[164:165], v[66:67], v[160:161], v[150:151] neg_lo:[0,0,1] neg_hi:[0,0,1]
	v_pk_mul_f32 v[160:161], v[78:79], v[160:161]
	v_pk_mul_f32 v[150:151], v[80:81], v[166:167]
	s_nop 0
	v_pk_fma_f32 v[150:151], v[68:69], v[154:155], v[150:151]
	v_pk_fma_f32 v[154:155], v[66:67], v[156:157], v[160:161]

;   DI void operator()(LAS unsigned char* lds, f32x4 (&acc)[2][2][4][2], int pm, int pn, int wr, int wc, int fr, int fq) const {
;     ...
;       for (int m = mb; m < mb + 2; ++m) {
;         const int s = s0 + ai * HALF + m * 16;
;         f32x4 v[2][2];
; #pragma unroll
;         for (int bj = 0; bj < 2; ++bj)
; #pragma unroll
;           for (int n = 0; n < 2; ++n) v[bj][n] = acc[ai][bj][m][n] * rstd[ai][m];
;         if (type < 2) {
;           float q = 0.f;
; #pragma unroll
;           for (int bj = 0; bj < 2; ++bj)
; #pragma unroll
;             for (int n = 0; n < 2; ++n) q += v[bj][n][0] * v[bj][n][0] + v[bj][n][1] * v[bj][n][1] + v[bj][n][2] * v[bj][n][2] + v[bj][n][3] * v[bj][n][3];
;           q += __shfl_xor(q, 16); q += __shfl_xor(q, 32);
;           float rn = rsqrtf(q * (1.0f / 64.0f) + EPS);
;           if (type == 0) rn *= 0.125f * LOG2E;
; #pragma unroll
;           for (int n = 0; n < 2; ++n) {
;             const f32x4 x1 = v[0][n] * g1[n] * rn, x2 = v[1][n] * g2[n] * rn;
;             v[0][n] = x1 * cs[m][n] - x2 * sn[m][n]; v[1][n] = x2 * cs[m][n] + x1 * sn[m][n];
;           }
.LBB0_482:
	v_pk_mul_f32 v[112:113], v[112:113], v[184:185] op_sel_hi:[1,0]
	v_pk_mul_f32 v[110:111], v[110:111], v[184:185] op_sel_hi:[1,0]
	v_pk_mul_f32 v[108:109], v[108:109], v[184:185] op_sel_hi:[1,0]
	v_pk_mul_f32 v[148:149], v[106:107], v[184:185] op_sel_hi:[1,0]
	v_pk_mul_f32 v[106:107], v[120:121], v[184:185] op_sel_hi:[1,0]
	v_pk_mul_f32 v[118:119], v[118:119], v[184:185] op_sel_hi:[1,0]
	v_pk_mul_f32 v[104:105], v[104:105], v[184:185] op_sel_hi:[1,0]
	s_and_b64 vcc, exec, s[44:45]
	v_pk_mul_f32 v[102:103], v[102:103], v[184:185] op_sel_hi:[1,0]
	s_cbranch_vccnz .LBB0_484
	v_mov_b32_e32 v150, v111
	v_mov_b32_e32 v151, v149
	v_mov_b32_e32 v120, v110
	v_mov_b32_e32 v121, v148
	v_pk_mul_f32 v[150:151], v[150:151], v[150:151]
	v_mov_b32_e32 v152, v103
	v_pk_fma_f32 v[120:121], v[120:121], v[120:121], v[150:151]
	v_mov_b32_e32 v150, v112
	v_mov_b32_e32 v151, v108
	v_pk_fma_f32 v[120:121], v[150:151], v[150:151], v[120:121]
	v_mov_b32_e32 v150, v113
	v_mov_b32_e32 v151, v109
	v_mov_b32_e32 v153, v119
	v_pk_fma_f32 v[120:121], v[150:151], v[150:151], v[120:121]
	v_mov_b32_e32 v150, v102
	v_mov_b32_e32 v151, v118
	v_pk_mul_f32 v[152:153], v[152:153], v[152:153]
	v_add_f32_e32 v120, v120, v121
	v_pk_fma_f32 v[150:151], v[150:151], v[150:151], v[152:153]
	v_mov_b32_e32 v152, v104
	v_mov_b32_e32 v153, v106
	v_pk_fma_f32 v[150:151], v[152:153], v[152:153], v[150:151]
	v_mov_b32_e32 v152, v105
	v_mov_b32_e32 v153, v107
	v_pk_fma_f32 v[150:151], v[152:153], v[152:153], v[150:151]
	v_xor_b32_e32 v121, 16, v224
	v_add_f32_e32 v120, v151, v120
	v_add_f32_e32 v120, v150, v120
	v_and_b32_e32 v150, 64, v224
	v_add_u32_e32 v150, 64, v150
	v_cmp_lt_i32_e32 vcc, v121, v150
	v_pk_mul_f32 v[110:111], v[110:111], v[14:15]
	v_pk_mul_f32 v[112:113], v[112:113], v[16:17]
	v_cndmask_b32_e32 v121, v224, v121, vcc
	v_lshlrev_b32_e32 v121, 2, v121
	s_waitcnt vmcnt(0) lgkmcnt(0)
	v_mov_b32_e32 v121, v120
	s_nop 1
	v_permlane16_swap_b32_e32 v120, v121
	v_pk_mul_f32 v[106:107], v[106:107], v[12:13]
	v_pk_mul_f32 v[102:103], v[102:103], v[2:3]
	v_pk_mul_f32 v[108:109], v[108:109], v[8:9]
	v_pk_mul_f32 v[104:105], v[104:105], v[4:5]
	s_waitcnt lgkmcnt(0)
	v_add_f32_e32 v120, v120, v121
	v_xor_b32_e32 v121, 32, v224
	v_cmp_lt_i32_e32 vcc, v121, v150
	s_nop 1
	v_cndmask_b32_e32 v121, v224, v121, vcc
	v_lshlrev_b32_e32 v121, 2, v121
	v_mov_b32_e32 v121, v120
	s_nop 1
	v_permlane32_swap_b32_e32 v120, v121
	s_waitcnt lgkmcnt(0)
	v_add_f32_e32 v120, v120, v121
	v_fmamk_f32 v120, v120, 0x3c800000, v227
	v_mul_f32_e32 v121, 0x4b800000, v120
	v_cmp_gt_f32_e32 vcc, s16, v120
	s_nop 1
	v_cndmask_b32_e32 v120, v120, v121, vcc
	v_rsq_f32_e32 v120, v120
	s_nop 0
	v_mul_f32_e32 v121, 0x45800000, v120
	v_cndmask_b32_e32 v120, v120, v121, vcc
	v_mul_f32_e32 v121, 0x3e38aa3b, v120
	v_cndmask_b32_e64 v120, v120, v121, s[96:97]
	v_pk_mul_f32 v[150:151], v[110:111], v[120:121] op_sel_hi:[1,0]
	v_pk_mul_f32 v[110:111], v[118:119], v[10:11]
	v_pk_mul_f32 v[152:153], v[112:113], v[120:121] op_sel_hi:[1,0]
	v_pk_mul_f32 v[118:119], v[110:111], v[120:121] op_sel_hi:[1,0]
	v_pk_mul_f32 v[106:107], v[106:107], v[120:121] op_sel_hi:[1,0]
	s_waitcnt vmcnt(0)
	v_pk_mul_f32 v[110:111], v[142:143], v[118:119]
	v_pk_mul_f32 v[142:143], v[142:143], v[150:151]
	v_pk_mul_f32 v[112:113], v[144:145], v[106:107]
	v_pk_fma_f32 v[110:111], v[134:135], v[150:151], v[110:111] neg_lo:[0,0,1] neg_hi:[0,0,1]
	v_pk_mul_f32 v[144:145], v[144:145], v[152:153]
	v_pk_fma_f32 v[118:119], v[134:135], v[118:119], v[142:143]
	v_pk_mul_f32 v[134:135], v[148:149], v[6:7]
	v_pk_mul_f32 v[102:103], v[102:103], v[120:121] op_sel_hi:[1,0]
	v_pk_fma_f32 v[112:113], v[136:137], v[152:153], v[112:113] neg_lo:[0,0,1] neg_hi:[0,0,1]
	v_pk_fma_f32 v[106:107], v[136:137], v[106:107], v[144:145]
	v_pk_mul_f32 v[134:135], v[134:135], v[120:121] op_sel_hi:[1,0]
	v_pk_mul_f32 v[136:137], v[108:109], v[120:121] op_sel_hi:[1,0]
	v_pk_mul_f32 v[104:105], v[104:105], v[120:121] op_sel_hi:[1,0]
	v_pk_mul_f32 v[120:121], v[130:131], v[102:103]
	v_pk_mul_f32 v[108:109], v[132:133], v[104:105]
	v_pk_fma_f32 v[148:149], v[114:115], v[134:135], v[120:121] neg_lo:[0,0,1] neg_hi:[0,0,1]
	v_pk_mul_f32 v[120:121], v[130:131], v[134:135]
	v_pk_mul_f32 v[130:131], v[132:133], v[136:137]
	v_pk_fma_f32 v[108:109], v[116:117], v[136:137], v[108:109] neg_lo:[0,0,1] neg_hi:[0,0,1]
	v_pk_fma_f32 v[104:105], v[116:117], v[104:105], v[130:131]
	v_pk_fma_f32 v[102:103], v[114:115], v[102:103], v[120:121]
; DI unsigned cvt_pk(float lo, float hi) { unsigned r; asm("v_cvt_pk_bf16_f32 %0, %1, %2" : "=v"(r) : "v"(lo), "v"(hi)); return r; }
;   DI void operator()(LAS unsigned char* lds, f32x4 (&acc)[2][2][4][2], int pm, int pn, int wr, int wc, int fr, int fq) const {
;     ...
;         const int s = s0 + ai * HALF + m * 16;
;         f32x4 v[2][2];
; #pragma unroll
;         for (int bj = 0; bj < 2; ++bj)
; #pragma unroll
;           for (int n = 0; n < 2; ++n) v[bj][n] = acc[ai][bj][m][n] * rstd[ai][m];
;         if (type < 2) {
;           float q = 0.f;
; #pragma unroll
;           for (int bj = 0; bj < 2; ++bj)
; #pragma unroll
;             for (int n = 0; n < 2; ++n) q += v[bj][n][0] * v[bj][n][0] + v[bj][n][1] * v[bj][n][1] + v[bj][n][2] * v[bj][n][2] + v[bj][n][3] * v[bj][n][3];
;           q += __shfl_xor(q, 16); q += __shfl_xor(q, 32);
;           float rn = rsqrtf(q * (1.0f / 64.0f) + EPS);
;           if (type == 0) rn *= 0.125f * LOG2E;
; #pragma unroll
;           for (int n = 0; n < 2; ++n) {
;             const f32x4 x1 = v[0][n] * g1[n] * rn, x2 = v[1][n] * g2[n] * rn;
;             v[0][n] = x1 * cs[m][n] - x2 * sn[m][n]; v[1][n] = x2 * cs[m][n] + x1 * sn[m][n];
;           }
;         }
;         bf16_t* rp = base + (size_t)s * 64 + 8 * fq;
; #pragma unroll
;         for (int bj = 0; bj < 2; ++bj) {
;           u32x4 w; w.x = cvt_pk(v[bj][0][0], v[bj][0][1]); w.y = cvt_pk(v[bj][0][2], v[bj][0][3]); w.z = cvt_pk(v[bj][1][0], v[bj][1][1]); w.w = cvt_pk(v[bj][1][2], v[bj][1][3]);
;           *(u32x4*)(rp + bj * 32) = w;
.LBB0_484:
	s_waitcnt vmcnt(0)
	v_lshlrev_b64 v[114:115], 7, v[146:147]
	v_lshl_add_u64 v[114:115], v[180:181], 0, v[114:115]
	v_cvt_pk_bf16_f32 v110, v110, v111
	v_cvt_pk_bf16_f32 v111, v112, v113
	v_cvt_pk_bf16_f32 v113, v108, v109
	v_cvt_pk_bf16_f32 v109, v106, v107
	v_mov_b32_e32 v106, v185
	v_cvt_pk_bf16_f32 v112, v148, v149
	global_store_dwordx4 v[114:115], v[110:113], off
	v_pk_mul_f32 v[60:61], v[60:61], v[106:107] op_sel_hi:[1,0]
	v_pk_mul_f32 v[52:53], v[52:53], v[106:107] op_sel_hi:[1,0]
	v_cvt_pk_bf16_f32 v110, v102, v103
	v_cvt_pk_bf16_f32 v111, v104, v105
	v_pk_mul_f32 v[102:103], v[58:59], v[106:107] op_sel_hi:[1,0]
	v_pk_mul_f32 v[58:59], v[56:57], v[106:107] op_sel_hi:[1,0]
	v_pk_mul_f32 v[104:105], v[54:55], v[106:107] op_sel_hi:[1,0]
	v_pk_mul_f32 v[54:55], v[64:65], v[106:107] op_sel_hi:[1,0]
	v_pk_mul_f32 v[56:57], v[62:63], v[106:107] op_sel_hi:[1,0]
	s_and_b64 vcc, exec, s[44:45]
	v_pk_mul_f32 v[50:51], v[50:51], v[106:107] op_sel_hi:[1,0]
	v_cvt_pk_bf16_f32 v108, v118, v119
	global_store_dwordx4 v[114:115], v[108:111], off offset:64
	s_cbranch_vccnz .LBB0_486
	v_mov_b32_e32 v64, v103
	v_mov_b32_e32 v65, v105
	v_mov_b32_e32 v62, v102
	v_mov_b32_e32 v63, v104
	v_pk_mul_f32 v[64:65], v[64:65], v[64:65]
	v_mov_b32_e32 v106, v51
	v_pk_fma_f32 v[62:63], v[62:63], v[62:63], v[64:65]
	v_mov_b32_e32 v64, v60
	v_mov_b32_e32 v65, v58
	v_pk_fma_f32 v[62:63], v[64:65], v[64:65], v[62:63]
	v_mov_b32_e32 v64, v61
	v_mov_b32_e32 v65, v59
	v_mov_b32_e32 v107, v57
	v_pk_fma_f32 v[62:63], v[64:65], v[64:65], v[62:63]
	v_mov_b32_e32 v64, v50
	v_mov_b32_e32 v65, v56
	v_pk_mul_f32 v[106:107], v[106:107], v[106:107]
	v_add_f32_e32 v62, v62, v63
	v_pk_fma_f32 v[64:65], v[64:65], v[64:65], v[106:107]
	v_mov_b32_e32 v106, v52
	v_mov_b32_e32 v107, v54
	v_pk_fma_f32 v[64:65], v[106:107], v[106:107], v[64:65]
	v_mov_b32_e32 v106, v53
	v_mov_b32_e32 v107, v55
	v_pk_fma_f32 v[64:65], v[106:107], v[106:107], v[64:65]
	v_xor_b32_e32 v63, 16, v224
	v_add_f32_e32 v62, v65, v62
	v_add_f32_e32 v62, v64, v62
	v_and_b32_e32 v64, 64, v224
	v_add_u32_e32 v64, 64, v64
	v_cmp_lt_i32_e32 vcc, v63, v64
	v_pk_mul_f32 v[56:57], v[56:57], v[10:11]
	v_pk_mul_f32 v[50:51], v[50:51], v[2:3]
	v_cndmask_b32_e32 v63, v224, v63, vcc
	v_lshlrev_b32_e32 v63, 2, v63
	s_waitcnt vmcnt(0) lgkmcnt(0)
	v_mov_b32_e32 v63, v62
	s_nop 1
	v_permlane16_swap_b32_e32 v62, v63
	v_pk_mul_f32 v[60:61], v[60:61], v[16:17]
	v_pk_mul_f32 v[54:55], v[54:55], v[12:13]
	v_pk_mul_f32 v[58:59], v[58:59], v[8:9]
	v_pk_mul_f32 v[52:53], v[52:53], v[4:5]
	s_waitcnt lgkmcnt(0)
	v_add_f32_e32 v62, v62, v63
	v_xor_b32_e32 v63, 32, v224
	v_cmp_lt_i32_e32 vcc, v63, v64
	v_pk_mul_f32 v[64:65], v[102:103], v[14:15]
	s_nop 0
	v_cndmask_b32_e32 v63, v224, v63, vcc
	v_lshlrev_b32_e32 v63, 2, v63
	v_mov_b32_e32 v63, v62
	s_nop 1
	v_permlane32_swap_b32_e32 v62, v63
	s_waitcnt lgkmcnt(0)
	v_add_f32_e32 v62, v62, v63
	v_fmamk_f32 v62, v62, 0x3c800000, v227
	v_mul_f32_e32 v63, 0x4b800000, v62
	v_cmp_gt_f32_e32 vcc, s16, v62
	s_nop 1
	v_cndmask_b32_e32 v62, v62, v63, vcc
	v_rsq_f32_e32 v62, v62
	s_nop 0
	v_mul_f32_e32 v63, 0x45800000, v62
	v_cndmask_b32_e32 v62, v62, v63, vcc
	v_mul_f32_e32 v63, 0x3e38aa3b, v62
	v_cndmask_b32_e64 v62, v62, v63, s[96:97]
	v_pk_mul_f32 v[56:57], v[56:57], v[62:63] op_sel_hi:[1,0]
	v_pk_mul_f32 v[64:65], v[64:65], v[62:63] op_sel_hi:[1,0]
	v_pk_mul_f32 v[102:103], v[90:91], v[56:57]
	v_pk_mul_f32 v[50:51], v[50:51], v[62:63] op_sel_hi:[1,0]
	v_pk_fma_f32 v[102:103], v[82:83], v[64:65], v[102:103] neg_lo:[0,0,1] neg_hi:[0,0,1]
	v_pk_mul_f32 v[64:65], v[90:91], v[64:65]
	v_pk_mul_f32 v[106:107], v[60:61], v[62:63] op_sel_hi:[1,0]
	v_pk_fma_f32 v[56:57], v[82:83], v[56:57], v[64:65]
	v_pk_mul_f32 v[64:65], v[104:105], v[6:7]
	v_pk_mul_f32 v[54:55], v[54:55], v[62:63] op_sel_hi:[1,0]
	v_pk_mul_f32 v[64:65], v[64:65], v[62:63] op_sel_hi:[1,0]
	v_pk_mul_f32 v[82:83], v[58:59], v[62:63] op_sel_hi:[1,0]
	v_pk_mul_f32 v[52:53], v[52:53], v[62:63] op_sel_hi:[1,0]
	v_pk_mul_f32 v[62:63], v[74:75], v[50:51]
	v_pk_mul_f32 v[60:61], v[92:93], v[54:55]
	v_pk_mul_f32 v[90:91], v[92:93], v[106:107]
	v_pk_mul_f32 v[58:59], v[76:77], v[52:53]
	v_pk_fma_f32 v[104:105], v[70:71], v[64:65], v[62:63] neg_lo:[0,0,1] neg_hi:[0,0,1]
	v_pk_mul_f32 v[62:63], v[74:75], v[64:65]
	v_pk_mul_f32 v[64:65], v[76:77], v[82:83]
	v_pk_fma_f32 v[60:61], v[84:85], v[106:107], v[60:61] neg_lo:[0,0,1] neg_hi:[0,0,1]
	v_pk_fma_f32 v[54:55], v[84:85], v[54:55], v[90:91]
	v_pk_fma_f32 v[58:59], v[72:73], v[82:83], v[58:59] neg_lo:[0,0,1] neg_hi:[0,0,1]
	v_pk_fma_f32 v[52:53], v[72:73], v[52:53], v[64:65]
	v_pk_fma_f32 v[50:51], v[70:71], v[50:51], v[62:63]

;   DI void operator()(LAS unsigned char* lds, f32x4 (&acc)[2][2][4][2], int pm, int pn, int wr, int wc, int fr, int fq) const {
;     ...
;       for (int m = mb; m < mb + 2; ++m) {
;         const int s = s0 + ai * HALF + m * 16;
;         f32x4 v[2][2];
; #pragma unroll
;         for (int bj = 0; bj < 2; ++bj)
; #pragma unroll
;           for (int n = 0; n < 2; ++n) v[bj][n] = acc[ai][bj][m][n] * rstd[ai][m];
;         if (type < 2) {
;           float q = 0.f;
; #pragma unroll
;           for (int bj = 0; bj < 2; ++bj)
; #pragma unroll
;             for (int n = 0; n < 2; ++n) q += v[bj][n][0] * v[bj][n][0] + v[bj][n][1] * v[bj][n][1] + v[bj][n][2] * v[bj][n][2] + v[bj][n][3] * v[bj][n][3];
;           q += __shfl_xor(q, 16); q += __shfl_xor(q, 32);
;           float rn = rsqrtf(q * (1.0f / 64.0f) + EPS);
;           if (type == 0) rn *= 0.125f * LOG2E;
; #pragma unroll
;           for (int n = 0; n < 2; ++n) {
;             const f32x4 x1 = v[0][n] * g1[n] * rn, x2 = v[1][n] * g2[n] * rn;
;             v[0][n] = x1 * cs[m][n] - x2 * sn[m][n]; v[1][n] = x2 * cs[m][n] + x1 * sn[m][n];
;           }
.LBB0_488:
	v_pk_mul_f32 v[44:45], v[44:45], v[178:179] op_sel_hi:[1,0]
	v_pk_mul_f32 v[42:43], v[42:43], v[178:179] op_sel_hi:[1,0]
	v_pk_mul_f32 v[40:41], v[40:41], v[178:179] op_sel_hi:[1,0]
	v_pk_mul_f32 v[52:53], v[38:39], v[178:179] op_sel_hi:[1,0]
	v_pk_mul_f32 v[38:39], v[48:49], v[178:179] op_sel_hi:[1,0]
	v_pk_mul_f32 v[46:47], v[46:47], v[178:179] op_sel_hi:[1,0]
	v_pk_mul_f32 v[36:37], v[36:37], v[178:179] op_sel_hi:[1,0]
	s_and_b64 vcc, exec, s[44:45]
	v_pk_mul_f32 v[34:35], v[34:35], v[178:179] op_sel_hi:[1,0]
	s_cbranch_vccnz .LBB0_490
	v_mov_b32_e32 v54, v43
	v_mov_b32_e32 v55, v53
	v_mov_b32_e32 v48, v42
	v_mov_b32_e32 v49, v52
	v_pk_mul_f32 v[54:55], v[54:55], v[54:55]
	v_mov_b32_e32 v56, v35
	v_pk_fma_f32 v[48:49], v[48:49], v[48:49], v[54:55]
	v_mov_b32_e32 v54, v44
	v_mov_b32_e32 v55, v40
	v_pk_fma_f32 v[48:49], v[54:55], v[54:55], v[48:49]
	v_mov_b32_e32 v54, v45
	v_mov_b32_e32 v55, v41
	v_mov_b32_e32 v57, v47
	v_pk_fma_f32 v[48:49], v[54:55], v[54:55], v[48:49]
	v_mov_b32_e32 v54, v34
	v_mov_b32_e32 v55, v46
	v_pk_mul_f32 v[56:57], v[56:57], v[56:57]
	v_add_f32_e32 v0, v48, v49
	v_pk_fma_f32 v[54:55], v[54:55], v[54:55], v[56:57]
	v_mov_b32_e32 v56, v36
	v_mov_b32_e32 v57, v38
	v_and_b32_e32 v49, 64, v224
	v_pk_fma_f32 v[54:55], v[56:57], v[56:57], v[54:55]
	v_mov_b32_e32 v56, v37
	v_mov_b32_e32 v57, v39
	v_xor_b32_e32 v48, 16, v224
	v_add_u32_e32 v49, 64, v49
	v_pk_fma_f32 v[54:55], v[56:57], v[56:57], v[54:55]
	v_cmp_lt_i32_e32 vcc, v48, v49
	v_add_f32_e32 v0, v55, v0
	v_add_f32_e32 v0, v54, v0
	v_cndmask_b32_e32 v48, v224, v48, vcc
	v_lshlrev_b32_e32 v48, 2, v48
	s_waitcnt vmcnt(0) lgkmcnt(0)
	v_mov_b32_e32 v48, v0
	s_nop 1
	v_permlane16_swap_b32_e32 v0, v48
	v_pk_mul_f32 v[42:43], v[42:43], v[14:15]
	v_pk_mul_f32 v[38:39], v[38:39], v[12:13]
	v_pk_mul_f32 v[44:45], v[44:45], v[16:17]
	v_pk_mul_f32 v[36:37], v[36:37], v[4:5]
	s_waitcnt lgkmcnt(0)
	v_add_f32_e32 v0, v0, v48
	v_xor_b32_e32 v48, 32, v224
	v_cmp_lt_i32_e32 vcc, v48, v49
	v_pk_mul_f32 v[34:35], v[34:35], v[2:3]
	v_pk_mul_f32 v[40:41], v[40:41], v[8:9]
	v_cndmask_b32_e32 v48, v224, v48, vcc
	v_lshlrev_b32_e32 v48, 2, v48
	v_mov_b32_e32 v48, v0
	s_nop 1
	v_permlane32_swap_b32_e32 v0, v48
	s_waitcnt lgkmcnt(0)
	v_add_f32_e32 v0, v0, v48
	v_fmamk_f32 v0, v0, 0x3c800000, v227
	v_mul_f32_e32 v48, 0x4b800000, v0
	v_cmp_gt_f32_e32 vcc, s16, v0
	s_nop 1
	v_cndmask_b32_e32 v0, v0, v48, vcc
	v_rsq_f32_e32 v0, v0
	s_nop 0
	v_mul_f32_e32 v48, 0x45800000, v0
	v_cndmask_b32_e32 v0, v0, v48, vcc
	v_mul_f32_e32 v48, 0x3e38aa3b, v0
	v_cndmask_b32_e64 v0, v0, v48, s[96:97]
	v_pk_mul_f32 v[48:49], v[42:43], v[0:1] op_sel_hi:[1,0]
	v_pk_mul_f32 v[42:43], v[46:47], v[10:11]
	v_pk_mul_f32 v[38:39], v[38:39], v[0:1] op_sel_hi:[1,0]
	v_pk_mul_f32 v[46:47], v[42:43], v[0:1] op_sel_hi:[1,0]
	v_pk_mul_f32 v[54:55], v[44:45], v[0:1] op_sel_hi:[1,0]
	s_waitcnt vmcnt(4)
	v_pk_mul_f32 v[42:43], v[138:139], v[46:47]
	v_pk_mul_f32 v[44:45], v[140:141], v[38:39]
	v_pk_fma_f32 v[42:43], v[126:127], v[48:49], v[42:43] neg_lo:[0,0,1] neg_hi:[0,0,1]
	v_pk_mul_f32 v[48:49], v[138:139], v[48:49]
	v_pk_fma_f32 v[44:45], v[128:129], v[54:55], v[44:45] neg_lo:[0,0,1] neg_hi:[0,0,1]
	v_pk_mul_f32 v[54:55], v[140:141], v[54:55]
	v_pk_fma_f32 v[46:47], v[126:127], v[46:47], v[48:49]
	v_pk_mul_f32 v[48:49], v[52:53], v[6:7]
	v_pk_mul_f32 v[36:37], v[36:37], v[0:1] op_sel_hi:[1,0]
	v_pk_mul_f32 v[34:35], v[34:35], v[0:1] op_sel_hi:[1,0]
	v_pk_fma_f32 v[38:39], v[128:129], v[38:39], v[54:55]
	v_pk_mul_f32 v[48:49], v[48:49], v[0:1] op_sel_hi:[1,0]
	v_pk_mul_f32 v[54:55], v[40:41], v[0:1] op_sel_hi:[1,0]
	v_pk_mul_f32 v[52:53], v[122:123], v[34:35]
	v_pk_mul_f32 v[40:41], v[124:125], v[36:37]
	v_pk_fma_f32 v[52:53], v[98:99], v[48:49], v[52:53] neg_lo:[0,0,1] neg_hi:[0,0,1]
	v_pk_fma_f32 v[40:41], v[100:101], v[54:55], v[40:41] neg_lo:[0,0,1] neg_hi:[0,0,1]
	v_pk_mul_f32 v[48:49], v[122:123], v[48:49]
	v_pk_mul_f32 v[54:55], v[124:125], v[54:55]
	v_pk_fma_f32 v[34:35], v[98:99], v[34:35], v[48:49]
	v_pk_fma_f32 v[36:37], v[100:101], v[36:37], v[54:55]
; DI unsigned cvt_pk(float lo, float hi) { unsigned r; asm("v_cvt_pk_bf16_f32 %0, %1, %2" : "=v"(r) : "v"(lo), "v"(hi)); return r; }
;   DI void operator()(LAS unsigned char* lds, f32x4 (&acc)[2][2][4][2], int pm, int pn, int wr, int wc, int fr, int fq) const {
;     ...
;         const int s = s0 + ai * HALF + m * 16;
;         f32x4 v[2][2];
; #pragma unroll
;         for (int bj = 0; bj < 2; ++bj)
; #pragma unroll
;           for (int n = 0; n < 2; ++n) v[bj][n] = acc[ai][bj][m][n] * rstd[ai][m];
;         if (type < 2) {
;           float q = 0.f;
; #pragma unroll
;           for (int bj = 0; bj < 2; ++bj)
; #pragma unroll
;             for (int n = 0; n < 2; ++n) q += v[bj][n][0] * v[bj][n][0] + v[bj][n][1] * v[bj][n][1] + v[bj][n][2] * v[bj][n][2] + v[bj][n][3] * v[bj][n][3];
;           q += __shfl_xor(q, 16); q += __shfl_xor(q, 32);
;           float rn = rsqrtf(q * (1.0f / 64.0f) + EPS);
;           if (type == 0) rn *= 0.125f * LOG2E;
; #pragma unroll
;           for (int n = 0; n < 2; ++n) {
;             const f32x4 x1 = v[0][n] * g1[n] * rn, x2 = v[1][n] * g2[n] * rn;
;             v[0][n] = x1 * cs[m][n] - x2 * sn[m][n]; v[1][n] = x2 * cs[m][n] + x1 * sn[m][n];
;           }
;         }
;         bf16_t* rp = base + (size_t)s * 64 + 8 * fq;
; #pragma unroll
;         for (int bj = 0; bj < 2; ++bj) {
;           u32x4 w; w.x = cvt_pk(v[bj][0][0], v[bj][0][1]); w.y = cvt_pk(v[bj][0][2], v[bj][0][3]); w.z = cvt_pk(v[bj][1][0], v[bj][1][1]); w.w = cvt_pk(v[bj][1][2], v[bj][1][3]);
;           *(u32x4*)(rp + bj * 32) = w;
.LBB0_490:
	v_lshlrev_b64 v[48:49], 7, v[50:51]
	v_lshl_add_u64 v[48:49], v[180:181], 0, v[48:49]
	v_cvt_pk_bf16_f32 v42, v42, v43
	v_cvt_pk_bf16_f32 v43, v44, v45
	v_mov_b32_e32 v0, v179
	v_cvt_pk_bf16_f32 v44, v52, v53
	v_cvt_pk_bf16_f32 v45, v40, v41
	global_store_dwordx4 v[48:49], v[42:45], off
	v_pk_mul_f32 v[28:29], v[28:29], v[0:1] op_sel_hi:[1,0]
	v_pk_mul_f32 v[20:21], v[20:21], v[0:1] op_sel_hi:[1,0]
	v_cvt_pk_bf16_f32 v42, v34, v35
	v_cvt_pk_bf16_f32 v43, v36, v37
	v_pk_mul_f32 v[34:35], v[26:27], v[0:1] op_sel_hi:[1,0]
	v_pk_mul_f32 v[26:27], v[24:25], v[0:1] op_sel_hi:[1,0]
	v_pk_mul_f32 v[36:37], v[22:23], v[0:1] op_sel_hi:[1,0]
	v_pk_mul_f32 v[22:23], v[32:33], v[0:1] op_sel_hi:[1,0]
	v_pk_mul_f32 v[24:25], v[30:31], v[0:1] op_sel_hi:[1,0]
	s_and_b64 vcc, exec, s[44:45]
	v_pk_mul_f32 v[18:19], v[18:19], v[0:1] op_sel_hi:[1,0]
	v_cvt_pk_bf16_f32 v40, v46, v47
	v_cvt_pk_bf16_f32 v41, v38, v39
	global_store_dwordx4 v[48:49], v[40:43], off offset:64
	s_cbranch_vccnz .LBB0_447
	v_mov_b32_e32 v32, v35
	v_mov_b32_e32 v33, v37
	v_mov_b32_e32 v30, v34
	v_mov_b32_e32 v31, v36
	v_pk_mul_f32 v[32:33], v[32:33], v[32:33]
	v_mov_b32_e32 v38, v19
	v_pk_fma_f32 v[30:31], v[30:31], v[30:31], v[32:33]
	v_mov_b32_e32 v32, v28
	v_mov_b32_e32 v33, v26
	v_pk_fma_f32 v[30:31], v[32:33], v[32:33], v[30:31]
	v_mov_b32_e32 v32, v29
	v_mov_b32_e32 v33, v27
	v_mov_b32_e32 v39, v25
	v_pk_fma_f32 v[30:31], v[32:33], v[32:33], v[30:31]
	v_mov_b32_e32 v32, v18
	v_mov_b32_e32 v33, v24
	v_pk_mul_f32 v[38:39], v[38:39], v[38:39]
	v_add_f32_e32 v0, v30, v31
	v_pk_fma_f32 v[32:33], v[32:33], v[32:33], v[38:39]
	v_mov_b32_e32 v38, v20
	v_mov_b32_e32 v39, v22
	v_and_b32_e32 v31, 64, v224
	v_pk_fma_f32 v[32:33], v[38:39], v[38:39], v[32:33]
	v_mov_b32_e32 v38, v21
	v_mov_b32_e32 v39, v23
	v_xor_b32_e32 v30, 16, v224
	v_add_u32_e32 v31, 64, v31
	v_pk_fma_f32 v[32:33], v[38:39], v[38:39], v[32:33]
	v_cmp_lt_i32_e32 vcc, v30, v31
	v_add_f32_e32 v0, v33, v0
	v_add_f32_e32 v0, v32, v0
	v_cndmask_b32_e32 v30, v224, v30, vcc
	v_lshlrev_b32_e32 v30, 2, v30
	s_waitcnt vmcnt(0) lgkmcnt(0)
	v_mov_b32_e32 v30, v0
	s_nop 1
	v_permlane16_swap_b32_e32 v0, v30
	v_pk_mul_f32 v[12:13], v[22:23], v[12:13]
	v_pk_mul_f32 v[10:11], v[24:25], v[10:11]
	v_pk_mul_f32 v[16:17], v[28:29], v[16:17]
	v_pk_mul_f32 v[14:15], v[34:35], v[14:15]
	s_waitcnt lgkmcnt(0)
	v_add_f32_e32 v0, v0, v30
	v_xor_b32_e32 v30, 32, v224
	v_cmp_lt_i32_e32 vcc, v30, v31
	v_pk_mul_f32 v[4:5], v[20:21], v[4:5]
	v_pk_mul_f32 v[2:3], v[18:19], v[2:3]
	v_cndmask_b32_e32 v30, v224, v30, vcc
	v_lshlrev_b32_e32 v30, 2, v30
	v_mov_b32_e32 v30, v0
	s_nop 1
	v_permlane32_swap_b32_e32 v0, v30
	v_pk_mul_f32 v[8:9], v[26:27], v[8:9]
	v_pk_mul_f32 v[6:7], v[36:37], v[6:7]
	s_waitcnt lgkmcnt(0)
	v_add_f32_e32 v0, v0, v30
	v_fmamk_f32 v0, v0, 0x3c800000, v227
	v_mul_f32_e32 v30, 0x4b800000, v0
	v_cmp_gt_f32_e32 vcc, s16, v0
	s_nop 1
	v_cndmask_b32_e32 v0, v0, v30, vcc
	v_rsq_f32_e32 v0, v0
	s_nop 0
	v_mul_f32_e32 v30, 0x45800000, v0
	v_cndmask_b32_e32 v0, v0, v30, vcc
	v_mul_f32_e32 v30, 0x3e38aa3b, v0
	v_cndmask_b32_e64 v0, v0, v30, s[96:97]
	v_pk_mul_f32 v[12:13], v[12:13], v[0:1] op_sel_hi:[1,0]
	v_pk_mul_f32 v[10:11], v[10:11], v[0:1] op_sel_hi:[1,0]
	v_pk_mul_f32 v[14:15], v[14:15], v[0:1] op_sel_hi:[1,0]
	v_pk_mul_f32 v[16:17], v[16:17], v[0:1] op_sel_hi:[1,0]
	s_waitcnt vmcnt(2)
	v_pk_mul_f32 v[22:23], v[94:95], v[10:11]
	v_pk_mul_f32 v[24:25], v[96:97], v[12:13]
	v_pk_fma_f32 v[34:35], v[86:87], v[14:15], v[22:23] neg_lo:[0,0,1] neg_hi:[0,0,1]
	v_pk_fma_f32 v[28:29], v[88:89], v[16:17], v[24:25] neg_lo:[0,0,1] neg_hi:[0,0,1]
	v_pk_mul_f32 v[14:15], v[94:95], v[14:15]
	v_pk_mul_f32 v[16:17], v[96:97], v[16:17]
	v_pk_mul_f32 v[4:5], v[4:5], v[0:1] op_sel_hi:[1,0]
	v_pk_mul_f32 v[2:3], v[2:3], v[0:1] op_sel_hi:[1,0]
	v_pk_fma_f32 v[22:23], v[88:89], v[12:13], v[16:17]
	v_pk_fma_f32 v[24:25], v[86:87], v[10:11], v[14:15]
	v_pk_mul_f32 v[6:7], v[6:7], v[0:1] op_sel_hi:[1,0]
	v_pk_mul_f32 v[8:9], v[8:9], v[0:1] op_sel_hi:[1,0]
	v_pk_mul_f32 v[10:11], v[78:79], v[2:3]
	v_pk_mul_f32 v[12:13], v[80:81], v[4:5]
	v_pk_fma_f32 v[36:37], v[66:67], v[6:7], v[10:11] neg_lo:[0,0,1] neg_hi:[0,0,1]
	v_pk_fma_f32 v[26:27], v[68:69], v[8:9], v[12:13] neg_lo:[0,0,1] neg_hi:[0,0,1]
	v_pk_mul_f32 v[6:7], v[78:79], v[6:7]
	v_pk_mul_f32 v[8:9], v[80:81], v[8:9]
	v_pk_fma_f32 v[18:19], v[66:67], v[2:3], v[6:7]
	v_pk_fma_f32 v[20:21], v[68:69], v[4:5], v[8:9]
	s_branch .LBB0_447
